# attention K-row RMS butterflies (lane^1,^2,^4) via DPP instead of ds_bpermute round trips
# speedup vs baseline: 1.0071x; 1.0071x over previous
.LBB0_318:
	s_or_b64 exec, exec, s[24:25]
	s_waitcnt vmcnt(2)
	v_lshlrev_b32_e32 v78, 16, v32
	v_and_b32_e32 v79, 0xffff0000, v32
	v_lshlrev_b32_e32 v74, 16, v33
	v_and_b32_e32 v75, 0xffff0000, v33
	v_pk_mul_f32 v[80:81], v[78:79], v[78:79]
	v_pk_mul_f32 v[76:77], v[74:75], v[74:75]
	v_add_f32_e32 v0, v80, v81
	v_lshlrev_b32_e32 v70, 16, v34
	v_and_b32_e32 v71, 0xffff0000, v34
	v_add_f32_e32 v0, v76, v0
	v_pk_mul_f32 v[72:73], v[70:71], v[70:71]
	v_add_f32_e32 v0, v77, v0
	v_lshlrev_b32_e32 v2, 16, v35
	v_and_b32_e32 v3, 0xffff0000, v35
	v_add_f32_e32 v0, v72, v0
	v_pk_mul_f32 v[68:69], v[2:3], v[2:3]
	v_add_f32_e32 v0, v73, v0
	v_add_f32_e32 v0, v68, v0
	v_add_f32_e32 v0, v69, v0
	s_nop 1
	v_mov_b32_dpp v68, v0 quad_perm:[1,0,3,2] row_mask:0xf bank_mask:0xf
	v_lshlrev_b32_e32 v86, 16, v28
	v_and_b32_e32 v87, 0xffff0000, v28
	v_lshlrev_b32_e32 v102, 16, v36
	v_and_b32_e32 v103, 0xffff0000, v36
	s_waitcnt lgkmcnt(0)
	v_add_f32_e32 v0, v0, v68
	s_nop 1
	v_mov_b32_dpp v68, v0 quad_perm:[2,3,0,1] row_mask:0xf bank_mask:0xf
	v_lshlrev_b32_e32 v82, 16, v29
	v_and_b32_e32 v83, 0xffff0000, v29
	v_pk_mul_f32 v[88:89], v[86:87], v[86:87]
	v_lshlrev_b32_e32 v98, 16, v37
	s_waitcnt lgkmcnt(0)
	v_add_f32_e32 v0, v0, v68
	s_nop 1
	v_mov_b32_dpp v68, v0 row_half_mirror row_mask:0xf bank_mask:0xf
	v_and_b32_e32 v99, 0xffff0000, v37
	v_pk_mul_f32 v[104:105], v[102:103], v[102:103]
	v_pk_mul_f32 v[84:85], v[82:83], v[82:83]
	v_pk_mul_f32 v[100:101], v[98:99], v[98:99]
	v_mov_b32_e32 v106, v104
	v_mov_b32_e32 v107, v88
	v_mov_b32_e32 v88, v105
	s_waitcnt lgkmcnt(0)
	v_add_f32_e32 v0, v0, v68
	v_lshlrev_b32_e32 v76, 16, v30
	v_and_b32_e32 v77, 0xffff0000, v30
	v_lshlrev_b32_e32 v94, 16, v38
	v_and_b32_e32 v95, 0xffff0000, v38
	v_pk_add_f32 v[88:89], v[106:107], v[88:89]
	v_mov_b32_e32 v104, v100
	v_mov_b32_e32 v105, v84
	v_fmamk_f32 v0, v0, 0x3c800000, v205
	v_pk_mul_f32 v[80:81], v[76:77], v[76:77]
	v_pk_mul_f32 v[96:97], v[94:95], v[94:95]
	v_pk_add_f32 v[88:89], v[104:105], v[88:89]
	v_mov_b32_e32 v84, v101
	v_lshlrev_b32_e32 v72, 16, v31
	v_mul_f32_e32 v68, 0x4b800000, v0
	v_cmp_gt_f32_e32 vcc, s83, v0
	v_and_b32_e32 v73, 0xffff0000, v31
	v_lshlrev_b32_e32 v90, 16, v39
	v_and_b32_e32 v91, 0xffff0000, v39
	v_pk_add_f32 v[84:85], v[84:85], v[88:89]
	v_mov_b32_e32 v88, v96
	v_mov_b32_e32 v89, v80
	v_cndmask_b32_e32 v0, v0, v68, vcc
	v_pk_mul_f32 v[68:69], v[72:73], v[72:73]
	v_pk_mul_f32 v[92:93], v[90:91], v[90:91]
	v_pk_add_f32 v[84:85], v[88:89], v[84:85]
	v_mov_b32_e32 v80, v97
	v_pk_add_f32 v[80:81], v[80:81], v[84:85]
	v_mov_b32_e32 v84, v92
	v_mov_b32_e32 v85, v68
	v_pk_add_f32 v[80:81], v[84:85], v[80:81]
	v_mov_b32_e32 v68, v93
	v_pk_add_f32 v[68:69], v[68:69], v[80:81]
	s_nop 1
	v_mov_b32_dpp v81, v69 quad_perm:[1,0,3,2] row_mask:0xf bank_mask:0xf
	s_nop 1
	v_mov_b32_dpp v80, v68 quad_perm:[1,0,3,2] row_mask:0xf bank_mask:0xf
	v_rsq_f32_e32 v0, v0
	s_mov_b32 s0, 0x358637bd
	s_mov_b32 s24, 0x3c800000
	v_lshlrev_b32_e32 v96, 16, v40
	v_mul_f32_e32 v84, 0x45800000, v0
	s_waitcnt lgkmcnt(0)
	v_pk_add_f32 v[80:81], v[68:69], v[80:81]
	v_cndmask_b32_e32 v0, v0, v84, vcc
	s_nop 1
	v_mov_b32_dpp v85, v81 quad_perm:[2,3,0,1] row_mask:0xf bank_mask:0xf
	s_nop 1
	v_mov_b32_dpp v84, v80 quad_perm:[2,3,0,1] row_mask:0xf bank_mask:0xf
	v_pk_mul_f32 v[74:75], v[0:1], v[74:75] op_sel_hi:[0,1]
	v_pk_mul_f32 v[78:79], v[0:1], v[78:79] op_sel_hi:[0,1]
	v_pk_mul_f32 v[74:75], v[10:11], v[74:75]
	v_pk_mul_f32 v[78:79], v[8:9], v[78:79]
	v_cvt_pk_bf16_f32 v69, v74, v75
	s_waitcnt lgkmcnt(0)
	v_pk_add_f32 v[74:75], v[80:81], v[84:85]
	v_cvt_pk_bf16_f32 v68, v78, v79
	s_nop 1
	v_mov_b32_dpp v79, v75 row_half_mirror row_mask:0xf bank_mask:0xf
	s_nop 1
	v_mov_b32_dpp v78, v74 row_half_mirror row_mask:0xf bank_mask:0xf
	v_mov_b64_e32 v[84:85], s[0:1]
	v_pk_mul_f32 v[70:71], v[0:1], v[70:71] op_sel_hi:[0,1]
	v_pk_mul_f32 v[2:3], v[0:1], v[2:3] op_sel_hi:[0,1]
	v_pk_mul_f32 v[70:71], v[4:5], v[70:71]
	s_waitcnt lgkmcnt(0)
	v_pk_add_f32 v[74:75], v[74:75], v[78:79]
	v_pk_mul_f32 v[2:3], v[6:7], v[2:3]
	v_pk_fma_f32 v[74:75], v[74:75], s[24:25], v[84:85] op_sel_hi:[1,0,0]
	v_cvt_pk_bf16_f32 v70, v70, v71
	v_mul_f32_e32 v0, 0x4b800000, v75
	v_cmp_gt_f32_e32 vcc, s83, v75
	v_cvt_pk_bf16_f32 v71, v2, v3
	ds_write_b128 v233, v[68:71]
	v_cndmask_b32_e32 v0, v75, v0, vcc
	v_rsq_f32_e32 v0, v0
	s_waitcnt vmcnt(0)
	v_and_b32_e32 v75, 0xffff0000, v64
	v_lshlrev_b32_e32 v92, 16, v41
	v_and_b32_e32 v93, 0xffff0000, v41
	v_mul_f32_e32 v2, 0x45800000, v0
	v_cndmask_b32_e32 v0, v0, v2, vcc
	v_pk_mul_f32 v[2:3], v[0:1], v[86:87] op_sel_hi:[0,1]
	v_pk_mul_f32 v[2:3], v[8:9], v[2:3]
	v_cmp_gt_f32_e32 vcc, s83, v74
	v_cvt_pk_bf16_f32 v68, v2, v3
	v_pk_mul_f32 v[2:3], v[0:1], v[82:83] op_sel_hi:[0,1]
	v_pk_mul_f32 v[2:3], v[10:11], v[2:3]
	v_and_b32_e32 v97, 0xffff0000, v40
	v_cvt_pk_bf16_f32 v69, v2, v3
	v_pk_mul_f32 v[2:3], v[0:1], v[76:77] op_sel_hi:[0,1]
	v_pk_mul_f32 v[2:3], v[4:5], v[2:3]
	v_lshlrev_b32_e32 v76, 16, v63
	v_cvt_pk_bf16_f32 v70, v2, v3
	v_pk_mul_f32 v[2:3], v[0:1], v[72:73] op_sel_hi:[0,1]
	v_mul_f32_e32 v0, 0x4b800000, v74
	v_cndmask_b32_e32 v0, v74, v0, vcc
	v_rsq_f32_e32 v0, v0
	v_pk_mul_f32 v[2:3], v[6:7], v[2:3]
	v_and_b32_e32 v77, 0xffff0000, v63
	v_cvt_pk_bf16_f32 v71, v2, v3
	v_mul_f32_e32 v2, 0x45800000, v0
	v_cndmask_b32_e32 v0, v0, v2, vcc
	v_pk_mul_f32 v[2:3], v[0:1], v[102:103] op_sel_hi:[0,1]
	v_pk_mul_f32 v[2:3], v[8:9], v[2:3]
	ds_write_b128 v234, v[68:71]
	v_cvt_pk_bf16_f32 v68, v2, v3
	v_pk_mul_f32 v[2:3], v[0:1], v[98:99] op_sel_hi:[0,1]
	v_pk_mul_f32 v[2:3], v[10:11], v[2:3]
	v_lshlrev_b32_e32 v72, 16, v65
	v_cvt_pk_bf16_f32 v69, v2, v3
	v_pk_mul_f32 v[2:3], v[0:1], v[94:95] op_sel_hi:[0,1]
	v_pk_mul_f32 v[2:3], v[4:5], v[2:3]
	v_and_b32_e32 v73, 0xffff0000, v65
	v_cvt_pk_bf16_f32 v70, v2, v3
	v_pk_mul_f32 v[2:3], v[0:1], v[90:91] op_sel_hi:[0,1]
	v_pk_mul_f32 v[2:3], v[6:7], v[2:3]
	v_lshlrev_b32_e32 v74, 16, v64
	v_cvt_pk_bf16_f32 v71, v2, v3
	ds_write_b128 v235, v[68:71]
	v_lshlrev_b32_e32 v68, 16, v67
	v_and_b32_e32 v69, 0xffff0000, v67
	v_lshlrev_b32_e32 v70, 16, v66
	v_and_b32_e32 v71, 0xffff0000, v66
	v_pk_mul_f32 v[78:79], v[68:69], v[68:69]
	v_pk_mul_f32 v[80:81], v[70:71], v[70:71]
	v_pk_fma_f32 v[100:101], v[76:77], v[76:77], v[78:79]
	v_lshlrev_b32_e32 v78, 16, v62
	v_and_b32_e32 v79, 0xffff0000, v62
	v_pk_fma_f32 v[102:103], v[78:79], v[78:79], v[80:81]
	v_lshlrev_b32_e32 v80, 16, v61
	v_and_b32_e32 v81, 0xffff0000, v61
	v_pk_mul_f32 v[82:83], v[72:73], v[72:73]
	v_mul_f32_e32 v0, v96, v96
	v_pk_fma_f32 v[104:105], v[80:81], v[80:81], v[82:83]
	v_lshlrev_b32_e32 v82, 16, v60
	v_and_b32_e32 v83, 0xffff0000, v60
	v_pk_mul_f32 v[106:107], v[74:75], v[74:75]
	v_pk_mul_f32 v[94:95], v[92:93], v[92:93]
	v_pk_fma_f32 v[98:99], v[96:97], v[96:97], v[0:1] op_sel_hi:[1,1,0]
	v_pk_fma_f32 v[106:107], v[82:83], v[82:83], v[106:107]
	v_lshlrev_b32_e32 v88, 16, v42
	v_and_b32_e32 v89, 0xffff0000, v42
	v_mov_b32_e32 v108, v106
	v_mov_b32_e32 v109, v94
	v_mov_b32_e32 v98, v107
	v_pk_mul_f32 v[90:91], v[88:89], v[88:89]
	v_pk_add_f32 v[98:99], v[108:109], v[98:99]
	v_mov_b32_e32 v94, v104
	v_lshlrev_b32_e32 v2, 16, v43
	v_and_b32_e32 v3, 0xffff0000, v43
	v_pk_add_f32 v[94:95], v[94:95], v[98:99]
	v_pk_mov_b32 v[98:99], v[104:105], v[90:91] op_sel:[1,0]
	v_pk_mul_f32 v[86:87], v[2:3], v[2:3]
	v_pk_add_f32 v[94:95], v[98:99], v[94:95]
	v_mov_b32_e32 v90, v102
	v_pk_add_f32 v[90:91], v[90:91], v[94:95]
	v_pk_mov_b32 v[94:95], v[102:103], v[86:87] op_sel:[1,0]
	v_mov_b32_e32 v86, v100
	v_pk_add_f32 v[90:91], v[94:95], v[90:91]
	v_and_b32_e32 v0, 0xffff, v44
	v_pk_add_f32 v[86:87], v[86:87], v[90:91]
	s_nop 1
	v_mov_b32_dpp v91, v87 quad_perm:[1,0,3,2] row_mask:0xf bank_mask:0xf
	v_mov_b32_e32 v90, v101
	v_lshl_or_b32 v110, v48, 16, v0
	v_lshrrev_b32_e32 v0, 16, v44
	s_mov_b32 s0, 0xffff0000
	s_waitcnt lgkmcnt(0)
	v_pk_add_f32 v[86:87], v[90:91], v[86:87]
	v_and_or_b32 v111, v48, s0, v0
	v_and_b32_e32 v0, 0xffff, v45
	s_nop 1
	v_mov_b32_dpp v91, v87 quad_perm:[2,3,0,1] row_mask:0xf bank_mask:0xf
	ds_bpermute_b32 v90, v177, v86
	v_lshl_or_b32 v134, v49, 16, v0
	v_lshrrev_b32_e32 v0, 16, v45
	v_and_or_b32 v135, v49, s0, v0
	v_and_b32_e32 v0, 0xffff, v46
	v_lshl_or_b32 v136, v50, 16, v0
	v_lshrrev_b32_e32 v0, 16, v46
	v_and_or_b32 v137, v50, s0, v0
	v_and_b32_e32 v0, 0xffff, v47
	v_lshl_or_b32 v138, v51, 16, v0
	v_lshrrev_b32_e32 v0, 16, v47
	s_waitcnt lgkmcnt(0)
	v_pk_add_f32 v[86:87], v[86:87], v[90:91]
	v_and_or_b32 v139, v51, s0, v0
	v_and_b32_e32 v0, 0xffff, v52
	s_nop 1
	v_mov_b32_dpp v91, v87 row_half_mirror row_mask:0xf bank_mask:0xf
	ds_bpermute_b32 v90, v178, v86
	v_lshl_or_b32 v140, v56, 16, v0
	v_lshrrev_b32_e32 v0, 16, v52
	v_and_or_b32 v94, v56, s0, v0
	v_and_b32_e32 v0, 0xffff, v53
	v_lshl_or_b32 v95, v57, 16, v0
	v_lshrrev_b32_e32 v0, 16, v53
	v_and_or_b32 v98, v57, s0, v0
	v_and_b32_e32 v0, 0xffff, v54
	v_lshl_or_b32 v99, v58, 16, v0
	v_lshrrev_b32_e32 v0, 16, v54
	s_waitcnt lgkmcnt(0)
	v_pk_add_f32 v[86:87], v[86:87], v[90:91]
	v_and_or_b32 v100, v58, s0, v0
	v_and_b32_e32 v0, 0xffff, v55
	v_pk_fma_f32 v[84:85], v[86:87], s[24:25], v[84:85] op_sel_hi:[1,0,0]
	v_lshl_or_b32 v101, v59, 16, v0
	v_mul_f32_e32 v0, 0x4b800000, v85
	v_cmp_gt_f32_e32 vcc, s83, v85
	s_add_i32 s59, s58, s46
	s_cmpk_gt_i32 s59, 0xfff
	v_cndmask_b32_e32 v0, v85, v0, vcc
	v_rsq_f32_e32 v0, v0
	v_lshrrev_b32_e32 v85, 16, v55
	v_and_or_b32 v85, v59, s0, v85
	s_mov_b32 s0, 0x800000
	v_mul_f32_e32 v86, 0x45800000, v0
	v_cndmask_b32_e32 v0, v0, v86, vcc
	v_pk_mul_f32 v[86:87], v[0:1], v[96:97] op_sel_hi:[0,1]
	v_pk_mul_f32 v[90:91], v[0:1], v[92:93] op_sel_hi:[0,1]
	v_pk_mul_f32 v[88:89], v[0:1], v[88:89] op_sel_hi:[0,1]
	v_pk_mul_f32 v[2:3], v[0:1], v[2:3] op_sel_hi:[0,1]
	v_pk_mul_f32 v[86:87], v[8:9], v[86:87]
	v_pk_mul_f32 v[90:91], v[10:11], v[90:91]
	v_pk_mul_f32 v[88:89], v[4:5], v[88:89]
	v_pk_mul_f32 v[2:3], v[6:7], v[2:3]
	v_cvt_pk_bf16_f32 v86, v86, v87
	v_cvt_pk_bf16_f32 v87, v90, v91
	v_cvt_pk_bf16_f32 v88, v88, v89
	v_cvt_pk_bf16_f32 v89, v2, v3
	v_add_u32_e32 v0, 0x9000, v237
	ds_write_b128 v236, v[86:89]
	ds_write2_b32 v0, v110, v111 offset1:132
	v_add_u32_e32 v0, 0x9400, v237
	ds_write2_b32 v0, v134, v135 offset0:8 offset1:140
	v_add_u32_e32 v0, 0x9800, v237
	ds_write2_b32 v0, v136, v137 offset0:16 offset1:148
	v_add_u32_e32 v0, 0x9c00, v237
	ds_write2_b32 v0, v138, v139 offset0:24 offset1:156
	v_add_u32_e32 v0, 0x9000, v238
	ds_write2_b32 v0, v140, v94 offset1:132
	v_add_u32_e32 v0, 0x9400, v238
	ds_write2_b32 v0, v95, v98 offset0:8 offset1:140
	v_add_u32_e32 v0, 0x9800, v238
	s_cselect_b64 s[28:29], -1, 0
	v_cmp_gt_f32_e64 s[82:83], s0, v84
	ds_write2_b32 v0, v99, v100 offset0:16 offset1:148
	v_add_u32_e32 v0, 0x9c00, v238
	s_and_b64 vcc, exec, s[28:29]
	ds_write2_b32 v0, v101, v85 offset0:24 offset1:156
	s_cbranch_vccnz .LBB0_333
	s_and_b32 s0, 0xffff, s47
	s_and_b32 s25, s59, 0x7f
	s_ashr_i32 s24, s59, 11
	s_lshr_b32 s0, s25, s0
	s_and_b32 s25, s25, s56
	s_bfe_u32 s34, s59, 0x40007
	s_lshl_b32 s35, s25, 7
	s_lshl_b32 s25, s24, 4
	s_or_b32 s48, s25, s34
	s_ashr_i32 s49, s48, 31
	s_lshl_b64 s[48:49], s[48:49], 14
	s_lshl_b64 s[52:53], s[0:1], s99
	s_add_u32 s52, s52, s48
	s_addc_u32 s53, s53, s49
	s_add_i32 s25, s35, 0xffffff80
	v_mov_b32_e32 v30, v1
	v_mov_b32_e32 v31, v1
	v_add_u32_e32 v0, s25, v129
	v_mov_b32_e32 v28, v1
	v_mov_b32_e32 v29, v1
	v_mov_b64_e32 v[34:35], v[30:31]
	v_cmp_lt_i32_e32 vcc, -1, v0
	v_mov_b64_e32 v[32:33], v[28:29]
	s_and_saveexec_b64 s[54:55], vcc
	s_cbranch_execz .LBB0_321
	v_lshl_add_u64 v[2:3], s[52:53], 0, v[0:1]
	v_lshlrev_b64 v[2:3], 7, v[2:3]
	v_lshl_add_u64 v[2:3], v[122:123], 0, v[2:3]
	global_load_dwordx4 v[32:35], v[2:3], off
